# phase loop header: phase kind / stage from packed immediates by scalar shift instead of two dependent table loads per phase
# speedup vs baseline: 1.0026x; 1.0026x over previous
; __global__ void __launch_bounds__(512) mega_fwd(Args a_) {
;     ...
;         if (ph > 0) { const int p = ph - 1, pair = p / (NE + NO), q = p % (NE + NO);
;             if (q < NE) { l = 2 * pair; kind = EVEN_K[q]; second = EVEN_S[q]; }
;             else { l = 2 * pair + 1; kind = ODD_K[q - NE]; second = ODD_S[q - NE]; } }
.LBB0_8:
	s_mov_b32 s90, s46
	s_mov_b32 s72, s93
	s_mov_b32 s91, s82
	v_mov_b32_e32 v186, v235
	s_ashr_i32 s2, s72, 31
	s_add_u32 s84, s0, s72
	s_addc_u32 s85, s1, s2
	s_mov_b32 s42, s38
	s_cmp_lt_i32 s38, 1
	s_mov_b32 s86, s93
	s_mov_b32 s83, s93
	s_mov_b32 s3, s93
	s_cbranch_scc1 .LBB0_13
	s_add_i32 s4, s42, -1
	s_mul_hi_u32 s2, s4, 0xf0f0f0f1
	s_lshr_b32 s3, s2, 4
	s_mul_i32 s2, s3, 17
	s_sub_i32 s6, s4, s2
	s_lshl_b32 s83, s3, 1
	s_cmp_lt_u32 s6, 10
	s_cbranch_scc1 .LBB0_11
	s_or_b32 s83, s83, 1
	s_add_i32 s6, s6, -10
	s_mov_b32 s4, 0x2189321
	s_mov_b32 s5, 0
	s_cmp_gt_u32 s6, 4
	s_cselect_b32 s3, 1, 0
	s_branch .LBB0_12
.LBB0_11:
	s_mov_b32 s4, 0x87654321
	s_mov_b32 s5, 0x21
	s_cmp_gt_u32 s6, 7
	s_cselect_b32 s3, 1, 0
.LBB0_12:
	s_lshl_b32 s2, s6, 2
	s_lshr_b64 s[4:5], s[4:5], s2
	s_and_b32 s86, s4, 15
	s_waitcnt lgkmcnt(0)
	v_mov_b32_e32 v1, s86
	v_mov_b32_e32 v0, s3
